# scan: 288-byte LDS rows for the Q''/K'' images (ds_read_b128 / ds_read_b64_tr_b16 fragment reads bank-conflict free), compact score exchange
# speedup vs baseline: 1.0311x; 1.0071x over previous
; #define LAS __attribute__((address_space(3)))
; __device__ void scan_phase(LAS unsigned char* lds, const Params& p) {
;     const int tid = threadIdx.x, w = __builtin_amdgcn_readfirstlane(tid >> 6), lane = tid & 63, ln = lane & 15, lq = lane >> 4;
;     constexpr int QST = 136, VST = 36;
;     constexpr int OFF_KS = 17408, OFF_V = 34816, BUFB = 39424;
;     LAS bf16_t* Sr = (LAS bf16_t*)(lds + 2 * BUFB);
;     LAS float* scs = (LAS float*)(lds + 2 * BUFB + 9216);
;     bf16_t* O = (bf16_t*)p.out;
;     bf16_t* Odummy = (bf16_t*)(p.ws + WS_A) + (size_t)blockIdx.x * 64 * 512;
;     const float* RT = (const float*)(p.ws + WS_RT);
;     const int eb = w & 1, tb = w >> 1;
;     if (w >= 4) __builtin_amdgcn_s_setprio(1);
;     for (int item = blockIdx.x; item < 256; item += gridDim.x) {
;         const int seq = (item & 7) + 8 * (item >> 5), es = (item >> 3) & 3;
;         const int dir = seq & 1, h = (seq >> 1) & 3, b = seq >> 3;
;         const char* Qx = (const char*)((const bf16_t*)(p.ws + (dir ? WS_QB : WS_QF)) + h * 128);
;         const char* Kx = (const char*)((const bf16_t*)(p.ws + (dir ? WS_KB : WS_KF)) + h * 128);
;         const char* Vx = (const char*)((const bf16_t*)(p.ws + WS_V) + h * 128 + es * 32);
;         const char* Rx = (const char*)(RT + (size_t)dir * NCHUNK * 512 + h * 128);
;         const char* Tx = (const char*)(RT + (size_t)(2 + dir) * NCHUNK * 512 + h * 128);
;         const unsigned qoff0 = (unsigned)((dir ? 63 - (tid >> 4) : (tid >> 4)) * 1024 + (tid & 15) * 16), qstep = dir ? (unsigned)-32768 : 32768u;
;         const unsigned voff = (unsigned)((dir ? 63 - (tid >> 3) : (tid >> 3)) * 1024 + (tid & 7) * 8), roff = (unsigned)(tid & 127) * 4u;
.LBB0_256:
	s_cmp_lt_i32 s72, 4
	s_cselect_b64 s[8:9], -1, 0
	s_waitcnt lgkmcnt(0)
	s_and_b64 s[38:39], s[8:9], s[6:7]
	s_andn2_b64 vcc, exec, s[38:39]
	s_cbranch_vccnz .LBB0_308
	v_lshrrev_b32_e32 v1, 6, v0
	s_nop 0
	v_readfirstlane_b32 s6, v1
	s_lshr_b32 s7, s6, 1
	s_and_b32 s8, s6, 1
	s_mov_b32 s9, s2
	s_load_dword s35, s[0:1], 0x98
	s_cmp_ge_u32 s7, 2
	s_cselect_b32 s11, 1, 0
	s_cmp_le_u32 s8, s7
	s_cselect_b32 s13, 1, 0
	s_add_u32 s3, s8, 2
	s_cmp_le_u32 s3, s7
	s_cselect_b32 s14, 1, 0
	v_and_b32_e32 v58, 15, v0
	v_bfe_u32 v59, v0, 4, 2
	v_lshrrev_b32_e32 v90, 2, v58
	v_and_b32_e32 v91, 3, v0
	v_and_b32_e32 v92, 63, v0
	v_lshlrev_b32_e32 v93, 2, v59
	v_add_u32_e32 v1, 0, v93
	v_cmp_le_u32_e64 s[94:95], v1, v58
	v_add_u32_e32 v1, 1, v93
	v_cmp_le_u32_e64 s[96:97], v1, v58
	v_add_u32_e32 v1, 2, v93
	v_cmp_le_u32_e64 s[98:99], v1, v58
	v_add_u32_e32 v1, 3, v93
	v_cmp_le_u32_e64 vcc, v1, v58
	s_cmp_eq_u32 s8, s7
	s_cselect_b64 s[76:77], s[94:95], -1
	s_cselect_b64 s[78:79], s[96:97], -1
	s_cselect_b64 s[80:81], s[98:99], -1
	s_cselect_b64 s[82:83], vcc, -1
	s_add_u32 s3, s8, 2
	s_cmp_eq_u32 s3, s7
	s_cselect_b64 s[84:85], s[94:95], -1
	s_cselect_b64 s[88:89], s[96:97], -1
	s_cselect_b64 s[90:91], s[98:99], -1
	s_cselect_b64 s[92:93], vcc, -1
	v_lshrrev_b32_e32 v1, 4, v0
	v_mul_u32_u24_e32 v60, 288, v1
	v_lshl_add_u32 v60, v58, 4, v60
	v_lshrrev_b32_e32 v1, 3, v0
	v_mul_u32_u24_e32 v63, 72, v1
	v_and_b32_e32 v1, 7, v0
	v_lshl_add_u32 v63, v1, 3, v63
	v_and_b32_e32 v1, 0x7f, v0
	v_lshlrev_b32_e32 v56, 2, v1
	s_cmp_lt_u32 s6, 2
	s_mov_b32 s4, 124416
	s_cselect_b32 s3, s4, 125952
	v_add_u32_e32 v78, s3, v56
	s_lshl_b32 s3, s7, 7
	s_add_u32 s3, s3, 124416
	v_lshl_add_u32 v79, v58, 2, s3
	s_mul_i32 s3, s7, 2304
	s_lshl_b32 s4, s8, 5
	s_add_u32 s3, s3, s4
	v_mul_u32_u24_e32 v1, 72, v58
	v_lshl_add_u32 v1, v59, 3, v1
	v_add_u32_e32 v1, s3, v1
	v_add_u32_e32 v80, 131088, v1
	v_add_u32_e32 v81, 140304, v1
	s_mul_i32 s3, s8, 4608
	v_mul_u32_u24_e32 v69, 288, v58
	v_lshl_add_u32 v69, v59, 4, v69
	v_add_u32_e32 v69, s3, v69
	s_mul_i32 s3, s7, 4608
	v_mul_u32_u24_e32 v66, 288, v58
	v_lshl_add_u32 v66, v59, 4, v66
	v_add_u32_e32 v66, s3, v66
	s_lshl_b32 s3, s7, 10
	s_sub_u32 s4, s7, 1
	s_lshl_b32 s4, s4, 11
	s_cmp_lt_u32 s7, 2
	s_cselect_b32 s3, s3, s4
	v_lshl_add_u32 v1, v92, 4, s3
	s_lshl_b32 s4, s8, 3
	v_add_u32_e32 v86, 149520, v1
	v_add_u32_e32 v84, s4, v86
	v_add_u32_e32 v87, 155664, v1
	v_add_u32_e32 v85, s4, v87
	v_lshl_add_u32 v1, v59, 3, v90
	v_mul_u32_u24_e32 v1, 72, v1
	v_lshl_add_u32 v1, v91, 3, v1
	s_lshl_b32 s4, s8, 5
	v_add_u32_e32 v1, s4, v1
	v_add_u32_e32 v82, 131088, v1
	v_add_u32_e32 v83, 140304, v1
	v_lshl_add_u32 v1, v59, 2, v90
	v_mul_u32_u24_e32 v72, 72, v1
	v_lshl_add_u32 v72, v91, 3, v72
	v_add_u32_e32 v72, s4, v72
	v_mul_u32_u24_e32 v75, 288, v1
	v_lshl_add_u32 v75, v91, 3, v75
	s_lshl_b32 s3, s7, 6
	v_add_u32_e32 v75, s3, v75
	v_add_u32_e32 v61, 41472, v60
	v_add_u32_e32 v62, 82944, v60
	v_add_u32_e32 v64, 41472, v63
	v_add_u32_e32 v65, 82944, v63
	v_add_u32_e32 v67, 41472, v66
	v_add_u32_e32 v68, 82944, v66
	v_add_u32_e32 v70, 41472, v69
	v_add_u32_e32 v71, 82944, v69
	v_add_u32_e32 v73, 41472, v72
	v_add_u32_e32 v74, 82944, v72
	v_add_u32_e32 v76, 41472, v75
	v_add_u32_e32 v77, 82944, v75
	s_waitcnt lgkmcnt(0)
	s_cmp_gt_u32 s9, 0xff
	s_cbranch_scc1 .Lsc5_done
; #define SCAN_BAR() asm volatile("s_waitcnt lgkmcnt(0)\n\ts_barrier" ::: "memory")
; __device__ void scan_phase(LAS unsigned char* lds, const Params& p) {
;     ...
;     for (int item = blockIdx.x; item < 256; item += gridDim.x) {
;         const int seq = (item & 7) + 8 * (item >> 5), es = (item >> 3) & 3;
;         const int dir = seq & 1, h = (seq >> 1) & 3, b = seq >> 3;
;         const char* Qx = (const char*)((const bf16_t*)(p.ws + (dir ? WS_QB : WS_QF)) + h * 128);
;         const char* Kx = (const char*)((const bf16_t*)(p.ws + (dir ? WS_KB : WS_KF)) + h * 128);
;         const char* Vx = (const char*)((const bf16_t*)(p.ws + WS_V) + h * 128 + es * 32);
;         const char* Rx = (const char*)(RT + (size_t)dir * NCHUNK * 512 + h * 128);
;         const char* Tx = (const char*)(RT + (size_t)(2 + dir) * NCHUNK * 512 + h * 128);
;         const unsigned qoff0 = (unsigned)((dir ? 63 - (tid >> 4) : (tid >> 4)) * 1024 + (tid & 15) * 16), qstep = dir ? (unsigned)-32768 : 32768u;
;         const unsigned voff = (unsigned)((dir ? 63 - (tid >> 3) : (tid >> 3)) * 1024 + (tid & 7) * 8), roff = (unsigned)(tid & 127) * 4u;
;         f32x4 S[2] = {(f32x4){0.f, 0.f, 0.f, 0.f}, (f32x4){0.f, 0.f, 0.f, 0.f}};
;         float tailp = 0.f;
;         u32x4 k4A[2], k4B[2], k4C[2], k4D[2]; u32x4 q4A[2], q4B[2], q4C[2], q4D[2]; u32x2 v4A, v4B, v4C, v4D; float rvA, tlA, rvB, tlB, rvC, tlC, rvD, tlD;
;     ...
;         SCAN_LOAD(0, k4A, q4A, v4A, rvA, tlA); SCAN_LOAD(1, k4B, q4B, v4B, rvB, tlB); SCAN_LOAD(2, k4C, q4C, v4C, rvC, tlC); SCAN_LOAD(3, k4D, q4D, v4D, rvD, tlD);
;         SCAN_STAGE(0, k4A, q4A, v4A, rvA, tlA); SCAN_LOAD(4, k4A, q4A, v4A, rvA, tlA);
;         SCAN_BAR();
.Lsc5_item:
	s_and_b32 s10, s9, 1
	s_lshr_b32 s3, s9, 1
	s_and_b32 s3, s3, 3
	s_lshr_b32 s4, s9, 5
	s_lshr_b32 s5, s9, 3
	s_and_b32 s5, s5, 3
	s_cmp_eq_u32 s10, 0
	s_cselect_b32 s15, 1, -1
	s_cselect_b32 s64, 0, 3
	s_cselect_b32 s65, -4, 0x43
	s_lshl_b32 s16, s4, 2
	s_add_u32 s16, s16, 0x200
	s_lshl_b32 s17, s4, 6
	s_add_u32 s16, s16, s64
	s_add_i32 s17, s17, s65
	s_lshl_b32 s3, s3, 8
	s_lshl_b32 s5, s5, 6
	s_mul_i32 s4, s3, 34816
	s_cmp_eq_u32 s10, 0
	s_mov_b32 s65, 0x5100000
	s_cselect_b32 s64, s65, 0x7300000
	s_add_u32 s64, s64, s4
	s_add_u32 s18, s70, s64
	s_addc_u32 s19, s71, 0
	s_cmp_eq_u32 s10, 0
	s_mov_b32 s65, 0x9500000
	s_cselect_b32 s64, s65, 0xb700000
	s_add_u32 s64, s64, s4
	s_add_u32 s20, s70, s64
	s_addc_u32 s21, s71, 0
	s_add_u32 s64, s3, s5
	s_add_u32 s65, s4, s5
	s_add_u32 s65, s65, 0xd900000
	s_add_u32 s22, s70, s65
	s_addc_u32 s23, s71, 0
	s_lshl_b32 s65, s10, 25
	s_add_u32 s64, s64, s65
	s_add_u32 s28, s68, s64
	s_addc_u32 s29, s69, 0
	s_mul_i32 s64, s10, 0x110000
	s_lshl_b32 s65, s3, 1
	s_add_u32 s64, s64, s65
	s_add_u32 s64, s64, 0x15b00000
	s_add_u32 s24, s70, s64
	s_addc_u32 s25, s71, 0
	s_add_u32 s26, s24, 0x220000
	s_addc_u32 s27, s25, 0
	s_lshl_b32 s64, s9, 16
	s_add_u32 s64, s64, 0xd00000
	s_add_u32 s30, s70, s64
	s_addc_u32 s31, s71, 0
	s_mul_i32 s5, s10, 63
	s_lshl_b32 s3, s7, 4
	v_add_u32_e32 v1, s3, v58
	v_xor_b32_e32 v1, s5, v1
	v_lshlrev_b32_e32 v1, 10, v1
	s_lshl_b32 s3, s8, 5
	v_lshl_add_u32 v57, v59, 3, v1
	v_add_u32_e32 v57, s3, v57
	v_lshrrev_b32_e32 v1, 4, v0
	v_xor_b32_e32 v93, s5, v1
	v_lshlrev_b32_e32 v93, 8, v93
	v_lshl_add_u32 v53, v58, 4, v93
	v_add_u32_e32 v1, 32, v1
	v_xor_b32_e32 v93, s5, v1
	v_lshlrev_b32_e32 v93, 8, v93
	v_lshl_add_u32 v54, v58, 4, v93
	v_lshrrev_b32_e32 v1, 3, v0
	v_xor_b32_e32 v1, s5, v1
	v_lshlrev_b32_e32 v1, 8, v1
	v_and_b32_e32 v93, 7, v0
	v_lshl_add_u32 v55, v93, 3, v1
	v_mov_b32_e32 v42, 0
	v_mov_b32_e32 v43, 0
	v_mov_b32_e32 v44, 0
	v_mov_b32_e32 v45, 0
	v_mov_b32_e32 v46, 0
	v_mov_b32_e32 v47, 0
	v_mov_b32_e32 v48, 0
	v_mov_b32_e32 v49, 0
	v_mov_b32_e32 v52, 0
	v_mov_b32_e32 v160, 0
	v_mov_b32_e32 v161, 0
	v_mov_b32_e32 v162, 0
	v_mov_b32_e32 v163, 0
	v_mov_b32_e32 v176, 0
	v_mov_b32_e32 v177, 0
	s_mov_b32 s3, 0
	s_cmp_lt_u32 s3, 4
	s_cselect_b32 s4, s16, s17
	s_mul_i32 s5, s3, s15
	s_add_i32 s4, s4, s5
	s_lshl_b32 s5, s4, 14
	s_lshl_b32 s4, s4, 11
	s_add_u32 s40, s18, s5
	s_addc_u32 s41, s19, 0
	s_add_u32 s42, s20, s5
	s_addc_u32 s43, s21, 0
	s_add_u32 s44, s22, s5
	s_addc_u32 s45, s23, 0
	s_add_u32 s46, s24, s4
	s_addc_u32 s47, s25, 0
	s_add_u32 s50, s26, s4
	s_addc_u32 s51, s27, 0
	global_load_dwordx4 v[2:5], v53, s[40:41]
	global_load_dwordx4 v[6:9], v54, s[40:41]
	global_load_dwordx4 v[10:13], v53, s[42:43]
	global_load_dwordx4 v[14:17], v54, s[42:43]
	global_load_dwordx2 v[18:19], v55, s[44:45]
	global_load_dword v20, v56, s[46:47]
	global_load_dword v21, v56, s[50:51]
	s_mov_b32 s3, 1
	s_cmp_lt_u32 s3, 4
	s_cselect_b32 s4, s16, s17
	s_mul_i32 s5, s3, s15
	s_add_i32 s4, s4, s5
	s_lshl_b32 s5, s4, 14
	s_lshl_b32 s4, s4, 11
	s_add_u32 s40, s18, s5
	s_addc_u32 s41, s19, 0
	s_add_u32 s42, s20, s5
	s_addc_u32 s43, s21, 0
	s_add_u32 s44, s22, s5
	s_addc_u32 s45, s23, 0
	s_add_u32 s46, s24, s4
	s_addc_u32 s47, s25, 0
	s_add_u32 s50, s26, s4
	s_addc_u32 s51, s27, 0
	global_load_dwordx4 v[22:25], v53, s[40:41]
	global_load_dwordx4 v[26:29], v54, s[40:41]
	global_load_dwordx4 v[30:33], v53, s[42:43]
	global_load_dwordx4 v[34:37], v54, s[42:43]
	global_load_dwordx2 v[38:39], v55, s[44:45]
	global_load_dword v40, v56, s[46:47]
	global_load_dword v41, v56, s[50:51]
	s_waitcnt vmcnt(0)
	ds_write_b128 v60, v[2:5] offset:0
	ds_write_b128 v60, v[6:9] offset:9216
	ds_write_b128 v60, v[10:13] offset:18432
	ds_write_b128 v60, v[14:17] offset:27648
	ds_write_b64 v63, v[18:19] offset:36864
	v_add_f32_e32 v92, v20, v52
	v_mul_f32_e32 v92, 0x3fb8aa3b, v92
	v_exp_f32_e32 v92, v92
	v_mov_b32_e32 v52, v21
	ds_write_b32 v78, v92 offset:0
	ds_write_b128 v61, v[22:25] offset:0
	ds_write_b128 v61, v[26:29] offset:9216
	ds_write_b128 v61, v[30:33] offset:18432
	ds_write_b128 v61, v[34:37] offset:27648
	ds_write_b64 v64, v[38:39] offset:36864
	v_add_f32_e32 v92, v40, v52
	v_mul_f32_e32 v92, 0x3fb8aa3b, v92
	v_exp_f32_e32 v92, v92
	v_mov_b32_e32 v52, v41
	ds_write_b32 v78, v92 offset:512
	s_mov_b32 s3, 2
	s_cmp_lt_u32 s3, 4
	s_cselect_b32 s4, s16, s17
	s_mul_i32 s5, s3, s15
	s_add_i32 s4, s4, s5
	s_lshl_b32 s5, s4, 14
	s_lshl_b32 s4, s4, 11
	s_add_u32 s40, s18, s5
	s_addc_u32 s41, s19, 0
	s_add_u32 s42, s20, s5
	s_addc_u32 s43, s21, 0
	s_add_u32 s44, s22, s5
	s_addc_u32 s45, s23, 0
	s_add_u32 s46, s24, s4
	s_addc_u32 s47, s25, 0
	s_add_u32 s50, s26, s4
	s_addc_u32 s51, s27, 0
	global_load_dwordx4 v[180:183], v53, s[40:41]
	global_load_dwordx4 v[184:187], v54, s[40:41]
	global_load_dwordx4 v[188:191], v53, s[42:43]
	global_load_dwordx4 v[192:195], v54, s[42:43]
	global_load_dwordx2 v[196:197], v55, s[44:45]
	global_load_dword v198, v56, s[46:47]
	global_load_dword v199, v56, s[50:51]
	global_store_dwordx2 v57, v[176:177], s[30:31]
	s_mov_b32 s3, 3
	s_cmp_lt_u32 s3, 4
	s_cselect_b32 s4, s16, s17
	s_mul_i32 s5, s3, s15
	s_add_i32 s4, s4, s5
	s_lshl_b32 s5, s4, 14
	s_lshl_b32 s4, s4, 11
	s_add_u32 s40, s18, s5
	s_addc_u32 s41, s19, 0
	s_add_u32 s42, s20, s5
	s_addc_u32 s43, s21, 0
	s_add_u32 s44, s22, s5
	s_addc_u32 s45, s23, 0
	s_add_u32 s46, s24, s4
	s_addc_u32 s47, s25, 0
	s_add_u32 s50, s26, s4
	s_addc_u32 s51, s27, 0
	global_load_dwordx4 v[2:5], v53, s[40:41]
	global_load_dwordx4 v[6:9], v54, s[40:41]
	global_load_dwordx4 v[10:13], v53, s[42:43]
	global_load_dwordx4 v[14:17], v54, s[42:43]
	global_load_dwordx2 v[18:19], v55, s[44:45]
	global_load_dword v20, v56, s[46:47]
	global_load_dword v21, v56, s[50:51]
	global_store_dwordx2 v57, v[176:177], s[30:31]
	s_waitcnt lgkmcnt(0)
	s_barrier
	ds_read_b32 v50, v79 offset:0
	ds_read_b32 v51, v79 offset:64
	ds_read_b128 v[96:99], v66 offset:0
	ds_read_b128 v[100:103], v66 offset:64
	ds_read_b128 v[104:107], v66 offset:128
	ds_read_b128 v[108:111], v66 offset:192
	s_cmp_eq_u32 s13, 0
	s_cbranch_scc1 .Lsc5_nox_p
	ds_read_b128 v[216:219], v69 offset:18432
	ds_read_b128 v[220:223], v69 offset:18496
	ds_read_b128 v[224:227], v69 offset:18560
	ds_read_b128 v[228:231], v69 offset:18624
.Lsc5_nox_p:
	s_cmp_eq_u32 s14, 0
	s_cbranch_scc1 .Lsc5_noy_p
	ds_read_b128 v[232:235], v69 offset:27648
	ds_read_b128 v[236:239], v69 offset:27712
	ds_read_b128 v[240:243], v69 offset:27776
	ds_read_b128 v[244:247], v69 offset:27840

.Lsc5_noy3_p:
	ds_write_b64 v84, v[160:161]
	s_cmp_eq_u32 s11, 0
	s_cbranch_scc1 .Lsc5_noyw_p
	ds_write_b64 v84, v[162:163] offset:1024

.Lsc5_loop:
	ds_read_b32 v50, v79 offset:512
	ds_read_b32 v51, v79 offset:576
	ds_read_b64_tr_b16 v[128:129], v72 offset:36864
	ds_read_b64_tr_b16 v[130:131], v72 offset:38016
	ds_read_b64_tr_b16 v[132:133], v72 offset:39168
	ds_read_b64_tr_b16 v[134:135], v72 offset:40320
	ds_read_b64_tr_b16 v[136:137], v75 offset:18432
	ds_read_b64_tr_b16 v[138:139], v75 offset:23040
	ds_read_b64_tr_b16 v[140:141], v75 offset:18464
	ds_read_b64_tr_b16 v[142:143], v75 offset:23072
	ds_read_b64_tr_b16 v[144:145], v75 offset:27648
	ds_read_b64_tr_b16 v[146:147], v75 offset:32256
	ds_read_b64_tr_b16 v[148:149], v75 offset:27680
	ds_read_b64_tr_b16 v[150:151], v75 offset:32288
	s_add_u32 s3, s34, 4
	s_min_u32 s3, s3, 67
	s_cmp_lt_u32 s3, 4
	s_cselect_b32 s4, s16, s17
	s_mul_i32 s5, s3, s15
	s_add_i32 s4, s4, s5
	s_lshl_b32 s5, s4, 14
	s_lshl_b32 s4, s4, 11
	s_add_u32 s40, s18, s5
	s_addc_u32 s41, s19, 0
	s_add_u32 s42, s20, s5
	s_addc_u32 s43, s21, 0
	s_add_u32 s44, s22, s5
	s_addc_u32 s45, s23, 0
	s_add_u32 s46, s24, s4
	s_addc_u32 s47, s25, 0
	s_add_u32 s50, s26, s4
	s_addc_u32 s51, s27, 0
	global_load_dwordx4 v[22:25], v53, s[40:41]
	global_load_dwordx4 v[26:29], v54, s[40:41]
	global_load_dwordx4 v[30:33], v53, s[42:43]
	global_load_dwordx4 v[34:37], v54, s[42:43]
	global_load_dwordx2 v[38:39], v55, s[44:45]
	global_load_dword v40, v56, s[46:47]
	global_load_dword v41, v56, s[50:51]
	s_waitcnt lgkmcnt(6)
	v_mfma_f32_16x16x32_bf16 v[42:45], v[128:131], v[136:139], v[42:45]
	ds_read_b64_tr_b16 v[112:113], v82 offset:0
	ds_read_b64_tr_b16 v[114:115], v82 offset:288
	ds_read_b64_tr_b16 v[116:117], v82 offset:2304
	ds_read_b64_tr_b16 v[118:119], v82 offset:2592
	s_waitcnt lgkmcnt(8)
	v_mfma_f32_16x16x32_bf16 v[46:49], v[128:131], v[140:143], v[46:49]
	ds_read_b64_tr_b16 v[120:121], v82 offset:4608
	ds_read_b64_tr_b16 v[122:123], v82 offset:4896
	ds_read_b64_tr_b16 v[124:125], v82 offset:6912
	ds_read_b64_tr_b16 v[126:127], v82 offset:7200
	s_waitcnt lgkmcnt(10)
	v_mfma_f32_16x16x32_bf16 v[42:45], v[132:135], v[144:147], v[42:45]
	ds_read_b128 v[164:167], v86
	ds_read_b128 v[168:171], v86 offset:1024
	s_waitcnt lgkmcnt(10)
	v_mfma_f32_16x16x32_bf16 v[46:49], v[132:135], v[148:151], v[46:49]
	s_waitcnt lgkmcnt(8)
	v_mfma_f32_16x16x32_bf16 v[172:175], v[112:115], v[96:99], 0
	ds_read_b128 v[200:203], v67 offset:0
	ds_read_b128 v[204:207], v67 offset:64
	s_waitcnt lgkmcnt(8)
	v_mfma_f32_16x16x32_bf16 v[172:175], v[116:119], v[100:103], v[172:175]
	ds_read_b128 v[208:211], v67 offset:128
	ds_read_b128 v[212:215], v67 offset:192
	s_waitcnt lgkmcnt(8)
	v_mfma_f32_16x16x32_bf16 v[172:175], v[120:123], v[104:107], v[172:175]
	s_cmp_eq_u32 s13, 0
	s_cbranch_scc1 .Lsc5_nox_0
	ds_read_b128 v[216:219], v70 offset:18432
	ds_read_b128 v[220:223], v70 offset:18496
	ds_read_b128 v[224:227], v70 offset:18560
	ds_read_b128 v[228:231], v70 offset:18624
.Lsc5_nox_0:
	s_waitcnt lgkmcnt(6)
	v_mfma_f32_16x16x32_bf16 v[172:175], v[124:127], v[108:111], v[172:175]
	s_cmp_eq_u32 s14, 0
	s_cbranch_scc1 .Lsc5_noy_0
	ds_read_b128 v[232:235], v70 offset:27648
	ds_read_b128 v[236:239], v70 offset:27712
	ds_read_b128 v[240:243], v70 offset:27776
	ds_read_b128 v[244:247], v70 offset:27840

.Lsc5_noy2_0:
	s_waitcnt vmcnt(16)
	ds_write_b128 v62, v[180:183] offset:0
	ds_write_b128 v62, v[184:187] offset:9216
	ds_write_b128 v62, v[188:191] offset:18432
	ds_write_b128 v62, v[192:195] offset:27648
	ds_write_b64 v65, v[196:197] offset:36864
	v_add_f32_e32 v92, v198, v52
	v_mul_f32_e32 v92, 0x3fb8aa3b, v92
	v_exp_f32_e32 v92, v92
	v_mov_b32_e32 v52, v199
	ds_write_b32 v78, v92 offset:1024
	global_store_dwordx2 v57, v[176:177], s[64:65]
	s_cmp_eq_u32 s13, 0
	s_cbranch_scc1 .Lsc5_nox3_0
	v_cndmask_b32_e64 v152, 0, v152, s[76:77]
	v_cndmask_b32_e64 v153, 0, v153, s[78:79]
	v_cndmask_b32_e64 v154, 0, v154, s[80:81]
	v_cndmask_b32_e64 v155, 0, v155, s[82:83]
	v_cvt_pk_bf16_f32 v160, v152, v153
	v_cvt_pk_bf16_f32 v161, v154, v155

.Lsc5_noy3_0:
	ds_write_b64 v85, v[160:161]
	s_cmp_eq_u32 s11, 0
	s_cbranch_scc1 .Lsc5_noyw_0
	ds_write_b64 v85, v[162:163] offset:1024
.Lsc5_noyw_0:
	s_waitcnt lgkmcnt(0)
	s_barrier
	ds_read_b32 v50, v79 offset:1024
	ds_read_b32 v51, v79 offset:1088
	ds_read_b64_tr_b16 v[128:129], v73 offset:36864
	ds_read_b64_tr_b16 v[130:131], v73 offset:38016
	ds_read_b64_tr_b16 v[132:133], v73 offset:39168
	ds_read_b64_tr_b16 v[134:135], v73 offset:40320
	ds_read_b64_tr_b16 v[136:137], v76 offset:18432
	ds_read_b64_tr_b16 v[138:139], v76 offset:23040
	ds_read_b64_tr_b16 v[140:141], v76 offset:18464
	ds_read_b64_tr_b16 v[142:143], v76 offset:23072
	ds_read_b64_tr_b16 v[144:145], v76 offset:27648
	ds_read_b64_tr_b16 v[146:147], v76 offset:32256
	ds_read_b64_tr_b16 v[148:149], v76 offset:27680
	ds_read_b64_tr_b16 v[150:151], v76 offset:32288
	s_add_u32 s3, s34, 5
	s_min_u32 s3, s3, 67
	s_cmp_lt_u32 s3, 4
	s_cselect_b32 s4, s16, s17
	s_mul_i32 s5, s3, s15
	s_add_i32 s4, s4, s5
	s_lshl_b32 s5, s4, 14
	s_lshl_b32 s4, s4, 11
	s_add_u32 s40, s18, s5
	s_addc_u32 s41, s19, 0
	s_add_u32 s42, s20, s5
	s_addc_u32 s43, s21, 0
	s_add_u32 s44, s22, s5
	s_addc_u32 s45, s23, 0
	s_add_u32 s46, s24, s4
	s_addc_u32 s47, s25, 0
	s_add_u32 s50, s26, s4
	s_addc_u32 s51, s27, 0
	global_load_dwordx4 v[180:183], v53, s[40:41]
	global_load_dwordx4 v[184:187], v54, s[40:41]
	global_load_dwordx4 v[188:191], v53, s[42:43]
	global_load_dwordx4 v[192:195], v54, s[42:43]
	global_load_dwordx2 v[196:197], v55, s[44:45]
	global_load_dword v198, v56, s[46:47]
	global_load_dword v199, v56, s[50:51]
	s_waitcnt lgkmcnt(6)
	v_mfma_f32_16x16x32_bf16 v[42:45], v[128:131], v[136:139], v[42:45]
	ds_read_b64_tr_b16 v[112:113], v83 offset:0
	ds_read_b64_tr_b16 v[114:115], v83 offset:288
	ds_read_b64_tr_b16 v[116:117], v83 offset:2304
	ds_read_b64_tr_b16 v[118:119], v83 offset:2592
	s_waitcnt lgkmcnt(8)
	v_mfma_f32_16x16x32_bf16 v[46:49], v[128:131], v[140:143], v[46:49]
	ds_read_b64_tr_b16 v[120:121], v83 offset:4608
	ds_read_b64_tr_b16 v[122:123], v83 offset:4896
	ds_read_b64_tr_b16 v[124:125], v83 offset:6912
	ds_read_b64_tr_b16 v[126:127], v83 offset:7200
	s_waitcnt lgkmcnt(10)
	v_mfma_f32_16x16x32_bf16 v[42:45], v[132:135], v[144:147], v[42:45]
	ds_read_b128 v[164:167], v87
	ds_read_b128 v[168:171], v87 offset:1024
	s_waitcnt lgkmcnt(10)
	v_mfma_f32_16x16x32_bf16 v[46:49], v[132:135], v[148:151], v[46:49]
	s_waitcnt lgkmcnt(8)
	v_mfma_f32_16x16x32_bf16 v[172:175], v[112:115], v[200:203], 0
	ds_read_b128 v[96:99], v68 offset:0
	ds_read_b128 v[100:103], v68 offset:64
	s_waitcnt lgkmcnt(8)
	v_mfma_f32_16x16x32_bf16 v[172:175], v[116:119], v[204:207], v[172:175]
	ds_read_b128 v[104:107], v68 offset:128
	ds_read_b128 v[108:111], v68 offset:192
	s_waitcnt lgkmcnt(8)
	v_mfma_f32_16x16x32_bf16 v[172:175], v[120:123], v[208:211], v[172:175]
	s_cmp_eq_u32 s13, 0
	s_cbranch_scc1 .Lsc5_nox_1
	ds_read_b128 v[216:219], v71 offset:18432
	ds_read_b128 v[220:223], v71 offset:18496
	ds_read_b128 v[224:227], v71 offset:18560
	ds_read_b128 v[228:231], v71 offset:18624
.Lsc5_nox_1:
	s_waitcnt lgkmcnt(6)
	v_mfma_f32_16x16x32_bf16 v[172:175], v[124:127], v[212:215], v[172:175]
	s_cmp_eq_u32 s14, 0
	s_cbranch_scc1 .Lsc5_noy_1
	ds_read_b128 v[232:235], v71 offset:27648
	ds_read_b128 v[236:239], v71 offset:27712
	ds_read_b128 v[240:243], v71 offset:27776
	ds_read_b128 v[244:247], v71 offset:27840

.Lsc5_noy2_1:
	s_waitcnt vmcnt(16)
	ds_write_b128 v60, v[2:5] offset:0
	ds_write_b128 v60, v[6:9] offset:9216
	ds_write_b128 v60, v[10:13] offset:18432
	ds_write_b128 v60, v[14:17] offset:27648
	ds_write_b64 v63, v[18:19] offset:36864
	v_add_f32_e32 v92, v20, v52
	v_mul_f32_e32 v92, 0x3fb8aa3b, v92
	v_exp_f32_e32 v92, v92
	v_mov_b32_e32 v52, v21
	ds_write_b32 v78, v92 offset:0
	global_store_dwordx2 v57, v[176:177], s[64:65]
	s_cmp_eq_u32 s13, 0
	s_cbranch_scc1 .Lsc5_nox3_1
	v_cndmask_b32_e64 v152, 0, v152, s[76:77]
	v_cndmask_b32_e64 v153, 0, v153, s[78:79]
	v_cndmask_b32_e64 v154, 0, v154, s[80:81]
	v_cndmask_b32_e64 v155, 0, v155, s[82:83]
	v_cvt_pk_bf16_f32 v160, v152, v153
	v_cvt_pk_bf16_f32 v161, v154, v155

.Lsc5_noyw_1:
	s_waitcnt lgkmcnt(0)
	s_barrier
	ds_read_b32 v50, v79 offset:0
	ds_read_b32 v51, v79 offset:64
	ds_read_b64_tr_b16 v[128:129], v74 offset:36864
	ds_read_b64_tr_b16 v[130:131], v74 offset:38016
	ds_read_b64_tr_b16 v[132:133], v74 offset:39168
	ds_read_b64_tr_b16 v[134:135], v74 offset:40320
	ds_read_b64_tr_b16 v[136:137], v77 offset:18432
	ds_read_b64_tr_b16 v[138:139], v77 offset:23040
	ds_read_b64_tr_b16 v[140:141], v77 offset:18464
	ds_read_b64_tr_b16 v[142:143], v77 offset:23072
	ds_read_b64_tr_b16 v[144:145], v77 offset:27648
	ds_read_b64_tr_b16 v[146:147], v77 offset:32256
	ds_read_b64_tr_b16 v[148:149], v77 offset:27680
	ds_read_b64_tr_b16 v[150:151], v77 offset:32288
	s_add_u32 s3, s34, 6
	s_min_u32 s3, s3, 67
	s_cmp_lt_u32 s3, 4
	s_cselect_b32 s4, s16, s17
	s_mul_i32 s5, s3, s15
	s_add_i32 s4, s4, s5
	s_lshl_b32 s5, s4, 14
	s_lshl_b32 s4, s4, 11
	s_add_u32 s40, s18, s5
	s_addc_u32 s41, s19, 0
	s_add_u32 s42, s20, s5
	s_addc_u32 s43, s21, 0
	s_add_u32 s44, s22, s5
	s_addc_u32 s45, s23, 0
	s_add_u32 s46, s24, s4
	s_addc_u32 s47, s25, 0
	s_add_u32 s50, s26, s4
	s_addc_u32 s51, s27, 0
	global_load_dwordx4 v[2:5], v53, s[40:41]
	global_load_dwordx4 v[6:9], v54, s[40:41]
	global_load_dwordx4 v[10:13], v53, s[42:43]
	global_load_dwordx4 v[14:17], v54, s[42:43]
	global_load_dwordx2 v[18:19], v55, s[44:45]
	global_load_dword v20, v56, s[46:47]
	global_load_dword v21, v56, s[50:51]
	s_waitcnt lgkmcnt(6)
	v_mfma_f32_16x16x32_bf16 v[42:45], v[128:131], v[136:139], v[42:45]
	ds_read_b64_tr_b16 v[112:113], v82 offset:0
	ds_read_b64_tr_b16 v[114:115], v82 offset:288
	ds_read_b64_tr_b16 v[116:117], v82 offset:2304
	ds_read_b64_tr_b16 v[118:119], v82 offset:2592
	s_waitcnt lgkmcnt(8)
	v_mfma_f32_16x16x32_bf16 v[46:49], v[128:131], v[140:143], v[46:49]
	ds_read_b64_tr_b16 v[120:121], v82 offset:4608
	ds_read_b64_tr_b16 v[122:123], v82 offset:4896
	ds_read_b64_tr_b16 v[124:125], v82 offset:6912
	ds_read_b64_tr_b16 v[126:127], v82 offset:7200
	s_waitcnt lgkmcnt(10)
	v_mfma_f32_16x16x32_bf16 v[42:45], v[132:135], v[144:147], v[42:45]
	ds_read_b128 v[164:167], v86
	ds_read_b128 v[168:171], v86 offset:1024
	s_waitcnt lgkmcnt(10)
	v_mfma_f32_16x16x32_bf16 v[46:49], v[132:135], v[148:151], v[46:49]
	s_waitcnt lgkmcnt(8)
	v_mfma_f32_16x16x32_bf16 v[172:175], v[112:115], v[96:99], 0
	ds_read_b128 v[200:203], v66 offset:0
	ds_read_b128 v[204:207], v66 offset:64
	s_waitcnt lgkmcnt(8)
	v_mfma_f32_16x16x32_bf16 v[172:175], v[116:119], v[100:103], v[172:175]
	ds_read_b128 v[208:211], v66 offset:128
	ds_read_b128 v[212:215], v66 offset:192
	s_waitcnt lgkmcnt(8)
	v_mfma_f32_16x16x32_bf16 v[172:175], v[120:123], v[104:107], v[172:175]
	s_cmp_eq_u32 s13, 0
	s_cbranch_scc1 .Lsc5_nox_2
	ds_read_b128 v[216:219], v69 offset:18432
	ds_read_b128 v[220:223], v69 offset:18496
	ds_read_b128 v[224:227], v69 offset:18560
	ds_read_b128 v[228:231], v69 offset:18624
.Lsc5_nox_2:
	s_waitcnt lgkmcnt(6)
	v_mfma_f32_16x16x32_bf16 v[172:175], v[124:127], v[108:111], v[172:175]
	s_cmp_eq_u32 s14, 0
	s_cbranch_scc1 .Lsc5_noy_2
	ds_read_b128 v[232:235], v69 offset:27648
	ds_read_b128 v[236:239], v69 offset:27712
	ds_read_b128 v[240:243], v69 offset:27776
	ds_read_b128 v[244:247], v69 offset:27840

.Lsc5_noy2_2:
	s_waitcnt vmcnt(16)
	ds_write_b128 v61, v[22:25] offset:0
	ds_write_b128 v61, v[26:29] offset:9216
	ds_write_b128 v61, v[30:33] offset:18432
	ds_write_b128 v61, v[34:37] offset:27648
	ds_write_b64 v64, v[38:39] offset:36864
	v_add_f32_e32 v92, v40, v52
	v_mul_f32_e32 v92, 0x3fb8aa3b, v92
	v_exp_f32_e32 v92, v92
	v_mov_b32_e32 v52, v41
	ds_write_b32 v78, v92 offset:512
	global_store_dwordx2 v57, v[176:177], s[64:65]
	s_cmp_eq_u32 s13, 0
	s_cbranch_scc1 .Lsc5_nox3_2
	v_cndmask_b32_e64 v152, 0, v152, s[76:77]
	v_cndmask_b32_e64 v153, 0, v153, s[78:79]
	v_cndmask_b32_e64 v154, 0, v154, s[80:81]
	v_cndmask_b32_e64 v155, 0, v155, s[82:83]
	v_cvt_pk_bf16_f32 v160, v152, v153
	v_cvt_pk_bf16_f32 v161, v154, v155

.Lsc5_noyw_2:
	s_waitcnt lgkmcnt(0)
	s_barrier
	ds_read_b32 v50, v79 offset:512
	ds_read_b32 v51, v79 offset:576
	ds_read_b64_tr_b16 v[128:129], v72 offset:36864
	ds_read_b64_tr_b16 v[130:131], v72 offset:38016
	ds_read_b64_tr_b16 v[132:133], v72 offset:39168
	ds_read_b64_tr_b16 v[134:135], v72 offset:40320
	ds_read_b64_tr_b16 v[136:137], v75 offset:18432
	ds_read_b64_tr_b16 v[138:139], v75 offset:23040
	ds_read_b64_tr_b16 v[140:141], v75 offset:18464
	ds_read_b64_tr_b16 v[142:143], v75 offset:23072
	ds_read_b64_tr_b16 v[144:145], v75 offset:27648
	ds_read_b64_tr_b16 v[146:147], v75 offset:32256
	ds_read_b64_tr_b16 v[148:149], v75 offset:27680
	ds_read_b64_tr_b16 v[150:151], v75 offset:32288
	s_add_u32 s3, s34, 7
	s_min_u32 s3, s3, 67
	s_cmp_lt_u32 s3, 4
	s_cselect_b32 s4, s16, s17
	s_mul_i32 s5, s3, s15
	s_add_i32 s4, s4, s5
	s_lshl_b32 s5, s4, 14
	s_lshl_b32 s4, s4, 11
	s_add_u32 s40, s18, s5
	s_addc_u32 s41, s19, 0
	s_add_u32 s42, s20, s5
	s_addc_u32 s43, s21, 0
	s_add_u32 s44, s22, s5
	s_addc_u32 s45, s23, 0
	s_add_u32 s46, s24, s4
	s_addc_u32 s47, s25, 0
	s_add_u32 s50, s26, s4
	s_addc_u32 s51, s27, 0
	global_load_dwordx4 v[22:25], v53, s[40:41]
	global_load_dwordx4 v[26:29], v54, s[40:41]
	global_load_dwordx4 v[30:33], v53, s[42:43]
	global_load_dwordx4 v[34:37], v54, s[42:43]
	global_load_dwordx2 v[38:39], v55, s[44:45]
	global_load_dword v40, v56, s[46:47]
	global_load_dword v41, v56, s[50:51]
	s_waitcnt lgkmcnt(6)
	v_mfma_f32_16x16x32_bf16 v[42:45], v[128:131], v[136:139], v[42:45]
	ds_read_b64_tr_b16 v[112:113], v83 offset:0
	ds_read_b64_tr_b16 v[114:115], v83 offset:288
	ds_read_b64_tr_b16 v[116:117], v83 offset:2304
	ds_read_b64_tr_b16 v[118:119], v83 offset:2592
	s_waitcnt lgkmcnt(8)
	v_mfma_f32_16x16x32_bf16 v[46:49], v[128:131], v[140:143], v[46:49]
	ds_read_b64_tr_b16 v[120:121], v83 offset:4608
	ds_read_b64_tr_b16 v[122:123], v83 offset:4896
	ds_read_b64_tr_b16 v[124:125], v83 offset:6912
	ds_read_b64_tr_b16 v[126:127], v83 offset:7200
	s_waitcnt lgkmcnt(10)
	v_mfma_f32_16x16x32_bf16 v[42:45], v[132:135], v[144:147], v[42:45]
	ds_read_b128 v[164:167], v87
	ds_read_b128 v[168:171], v87 offset:1024
	s_waitcnt lgkmcnt(10)
	v_mfma_f32_16x16x32_bf16 v[46:49], v[132:135], v[148:151], v[46:49]
	s_waitcnt lgkmcnt(8)
	v_mfma_f32_16x16x32_bf16 v[172:175], v[112:115], v[200:203], 0
	ds_read_b128 v[96:99], v67 offset:0
	ds_read_b128 v[100:103], v67 offset:64
	s_waitcnt lgkmcnt(8)
	v_mfma_f32_16x16x32_bf16 v[172:175], v[116:119], v[204:207], v[172:175]
	ds_read_b128 v[104:107], v67 offset:128
	ds_read_b128 v[108:111], v67 offset:192
	s_waitcnt lgkmcnt(8)
	v_mfma_f32_16x16x32_bf16 v[172:175], v[120:123], v[208:211], v[172:175]
	s_cmp_eq_u32 s13, 0
	s_cbranch_scc1 .Lsc5_nox_3
	ds_read_b128 v[216:219], v70 offset:18432
	ds_read_b128 v[220:223], v70 offset:18496
	ds_read_b128 v[224:227], v70 offset:18560
	ds_read_b128 v[228:231], v70 offset:18624
.Lsc5_nox_3:
	s_waitcnt lgkmcnt(6)
	v_mfma_f32_16x16x32_bf16 v[172:175], v[124:127], v[212:215], v[172:175]
	s_cmp_eq_u32 s14, 0
	s_cbranch_scc1 .Lsc5_noy_3
	ds_read_b128 v[232:235], v70 offset:27648
	ds_read_b128 v[236:239], v70 offset:27712
	ds_read_b128 v[240:243], v70 offset:27776
	ds_read_b128 v[244:247], v70 offset:27840

.Lsc5_noyw_3:
	s_waitcnt lgkmcnt(0)
	s_barrier
	ds_read_b32 v50, v79 offset:1024
	ds_read_b32 v51, v79 offset:1088
	ds_read_b64_tr_b16 v[128:129], v73 offset:36864
	ds_read_b64_tr_b16 v[130:131], v73 offset:38016
	ds_read_b64_tr_b16 v[132:133], v73 offset:39168
	ds_read_b64_tr_b16 v[134:135], v73 offset:40320
	ds_read_b64_tr_b16 v[136:137], v76 offset:18432
	ds_read_b64_tr_b16 v[138:139], v76 offset:23040
	ds_read_b64_tr_b16 v[140:141], v76 offset:18464
	ds_read_b64_tr_b16 v[142:143], v76 offset:23072
	ds_read_b64_tr_b16 v[144:145], v76 offset:27648
	ds_read_b64_tr_b16 v[146:147], v76 offset:32256
	ds_read_b64_tr_b16 v[148:149], v76 offset:27680
	ds_read_b64_tr_b16 v[150:151], v76 offset:32288
	s_add_u32 s3, s34, 8
	s_min_u32 s3, s3, 67
	s_cmp_lt_u32 s3, 4
	s_cselect_b32 s4, s16, s17
	s_mul_i32 s5, s3, s15
	s_add_i32 s4, s4, s5
	s_lshl_b32 s5, s4, 14
	s_lshl_b32 s4, s4, 11
	s_add_u32 s40, s18, s5
	s_addc_u32 s41, s19, 0
	s_add_u32 s42, s20, s5
	s_addc_u32 s43, s21, 0
	s_add_u32 s44, s22, s5
	s_addc_u32 s45, s23, 0
	s_add_u32 s46, s24, s4
	s_addc_u32 s47, s25, 0
	s_add_u32 s50, s26, s4
	s_addc_u32 s51, s27, 0
	global_load_dwordx4 v[180:183], v53, s[40:41]
	global_load_dwordx4 v[184:187], v54, s[40:41]
	global_load_dwordx4 v[188:191], v53, s[42:43]
	global_load_dwordx4 v[192:195], v54, s[42:43]
	global_load_dwordx2 v[196:197], v55, s[44:45]
	global_load_dword v198, v56, s[46:47]
	global_load_dword v199, v56, s[50:51]
	s_waitcnt lgkmcnt(6)
	v_mfma_f32_16x16x32_bf16 v[42:45], v[128:131], v[136:139], v[42:45]
	ds_read_b64_tr_b16 v[112:113], v82 offset:0
	ds_read_b64_tr_b16 v[114:115], v82 offset:288
	ds_read_b64_tr_b16 v[116:117], v82 offset:2304
	ds_read_b64_tr_b16 v[118:119], v82 offset:2592
	s_waitcnt lgkmcnt(8)
	v_mfma_f32_16x16x32_bf16 v[46:49], v[128:131], v[140:143], v[46:49]
	ds_read_b64_tr_b16 v[120:121], v82 offset:4608
	ds_read_b64_tr_b16 v[122:123], v82 offset:4896
	ds_read_b64_tr_b16 v[124:125], v82 offset:6912
	ds_read_b64_tr_b16 v[126:127], v82 offset:7200
	s_waitcnt lgkmcnt(10)
	v_mfma_f32_16x16x32_bf16 v[42:45], v[132:135], v[144:147], v[42:45]
	ds_read_b128 v[164:167], v86
	ds_read_b128 v[168:171], v86 offset:1024
	s_waitcnt lgkmcnt(10)
	v_mfma_f32_16x16x32_bf16 v[46:49], v[132:135], v[148:151], v[46:49]
	s_waitcnt lgkmcnt(8)
	v_mfma_f32_16x16x32_bf16 v[172:175], v[112:115], v[96:99], 0
	ds_read_b128 v[200:203], v68 offset:0
	ds_read_b128 v[204:207], v68 offset:64
	s_waitcnt lgkmcnt(8)
	v_mfma_f32_16x16x32_bf16 v[172:175], v[116:119], v[100:103], v[172:175]
	ds_read_b128 v[208:211], v68 offset:128
	ds_read_b128 v[212:215], v68 offset:192
	s_waitcnt lgkmcnt(8)
	v_mfma_f32_16x16x32_bf16 v[172:175], v[120:123], v[104:107], v[172:175]
	s_cmp_eq_u32 s13, 0
	s_cbranch_scc1 .Lsc5_nox_4
	ds_read_b128 v[216:219], v71 offset:18432
	ds_read_b128 v[220:223], v71 offset:18496
	ds_read_b128 v[224:227], v71 offset:18560
	ds_read_b128 v[228:231], v71 offset:18624
.Lsc5_nox_4:
	s_waitcnt lgkmcnt(6)
	v_mfma_f32_16x16x32_bf16 v[172:175], v[124:127], v[108:111], v[172:175]
	s_cmp_eq_u32 s14, 0
	s_cbranch_scc1 .Lsc5_noy_4
	ds_read_b128 v[232:235], v71 offset:27648
	ds_read_b128 v[236:239], v71 offset:27712
	ds_read_b128 v[240:243], v71 offset:27776
	ds_read_b128 v[244:247], v71 offset:27840

.Lsc5_noyw_4:
	s_waitcnt lgkmcnt(0)
	s_barrier
	ds_read_b32 v50, v79 offset:0
	ds_read_b32 v51, v79 offset:64
	ds_read_b64_tr_b16 v[128:129], v74 offset:36864
	ds_read_b64_tr_b16 v[130:131], v74 offset:38016
	ds_read_b64_tr_b16 v[132:133], v74 offset:39168
	ds_read_b64_tr_b16 v[134:135], v74 offset:40320
	ds_read_b64_tr_b16 v[136:137], v77 offset:18432
	ds_read_b64_tr_b16 v[138:139], v77 offset:23040
	ds_read_b64_tr_b16 v[140:141], v77 offset:18464
	ds_read_b64_tr_b16 v[142:143], v77 offset:23072
	ds_read_b64_tr_b16 v[144:145], v77 offset:27648
	ds_read_b64_tr_b16 v[146:147], v77 offset:32256
	ds_read_b64_tr_b16 v[148:149], v77 offset:27680
	ds_read_b64_tr_b16 v[150:151], v77 offset:32288
	s_add_u32 s3, s34, 9
	s_min_u32 s3, s3, 67
	s_cmp_lt_u32 s3, 4
	s_cselect_b32 s4, s16, s17
	s_mul_i32 s5, s3, s15
	s_add_i32 s4, s4, s5
	s_lshl_b32 s5, s4, 14
	s_lshl_b32 s4, s4, 11
	s_add_u32 s40, s18, s5
	s_addc_u32 s41, s19, 0
	s_add_u32 s42, s20, s5
	s_addc_u32 s43, s21, 0
	s_add_u32 s44, s22, s5
	s_addc_u32 s45, s23, 0
	s_add_u32 s46, s24, s4
	s_addc_u32 s47, s25, 0
	s_add_u32 s50, s26, s4
	s_addc_u32 s51, s27, 0
	global_load_dwordx4 v[2:5], v53, s[40:41]
	global_load_dwordx4 v[6:9], v54, s[40:41]
	global_load_dwordx4 v[10:13], v53, s[42:43]
	global_load_dwordx4 v[14:17], v54, s[42:43]
	global_load_dwordx2 v[18:19], v55, s[44:45]
	global_load_dword v20, v56, s[46:47]
	global_load_dword v21, v56, s[50:51]
	s_waitcnt lgkmcnt(6)
	v_mfma_f32_16x16x32_bf16 v[42:45], v[128:131], v[136:139], v[42:45]
	ds_read_b64_tr_b16 v[112:113], v83 offset:0
	ds_read_b64_tr_b16 v[114:115], v83 offset:288
	ds_read_b64_tr_b16 v[116:117], v83 offset:2304
	ds_read_b64_tr_b16 v[118:119], v83 offset:2592
	s_waitcnt lgkmcnt(8)
	v_mfma_f32_16x16x32_bf16 v[46:49], v[128:131], v[140:143], v[46:49]
	ds_read_b64_tr_b16 v[120:121], v83 offset:4608
	ds_read_b64_tr_b16 v[122:123], v83 offset:4896
	ds_read_b64_tr_b16 v[124:125], v83 offset:6912
	ds_read_b64_tr_b16 v[126:127], v83 offset:7200
	s_waitcnt lgkmcnt(10)
	v_mfma_f32_16x16x32_bf16 v[42:45], v[132:135], v[144:147], v[42:45]
	ds_read_b128 v[164:167], v87
	ds_read_b128 v[168:171], v87 offset:1024
	s_waitcnt lgkmcnt(10)
	v_mfma_f32_16x16x32_bf16 v[46:49], v[132:135], v[148:151], v[46:49]
	s_waitcnt lgkmcnt(8)
	v_mfma_f32_16x16x32_bf16 v[172:175], v[112:115], v[200:203], 0
	ds_read_b128 v[96:99], v66 offset:0
	ds_read_b128 v[100:103], v66 offset:64
	s_waitcnt lgkmcnt(8)
	v_mfma_f32_16x16x32_bf16 v[172:175], v[116:119], v[204:207], v[172:175]
	ds_read_b128 v[104:107], v66 offset:128
	ds_read_b128 v[108:111], v66 offset:192
	s_waitcnt lgkmcnt(8)
	v_mfma_f32_16x16x32_bf16 v[172:175], v[120:123], v[208:211], v[172:175]
	s_cmp_eq_u32 s13, 0
	s_cbranch_scc1 .Lsc5_nox_5
	ds_read_b128 v[216:219], v69 offset:18432
	ds_read_b128 v[220:223], v69 offset:18496
	ds_read_b128 v[224:227], v69 offset:18560
	ds_read_b128 v[228:231], v69 offset:18624
.Lsc5_nox_5:
	s_waitcnt lgkmcnt(6)
	v_mfma_f32_16x16x32_bf16 v[172:175], v[124:127], v[212:215], v[172:175]
	s_cmp_eq_u32 s14, 0
	s_cbranch_scc1 .Lsc5_noy_5
	ds_read_b128 v[232:235], v69 offset:27648
	ds_read_b128 v[236:239], v69 offset:27712
	ds_read_b128 v[240:243], v69 offset:27776
	ds_read_b128 v[244:247], v69 offset:27840

; #define SCAN_BAR() asm volatile("s_waitcnt lgkmcnt(0)\n\ts_barrier" ::: "memory")
; __device__ void scan_phase(LAS unsigned char* lds, const Params& p) {
;     ...
;         SCAN_LOAD(0, k4A, q4A, v4A, rvA, tlA); SCAN_LOAD(1, k4B, q4B, v4B, rvB, tlB); SCAN_LOAD(2, k4C, q4C, v4C, rvC, tlC); SCAN_LOAD(3, k4D, q4D, v4D, rvD, tlD);
;         SCAN_STAGE(0, k4A, q4A, v4A, rvA, tlA); SCAN_LOAD(4, k4A, q4A, v4A, rvA, tlA);
;         SCAN_BAR();
; #pragma unroll 1
;         for (int n0 = 0; n0 < 68; n0 += 4) {
.Lsc5_noyw_5:
	s_waitcnt lgkmcnt(0)
	s_barrier
	s_add_u32 s34, s34, 6
	s_cmp_lt_u32 s34, 66
	s_cbranch_scc1 .Lsc5_loop
	ds_read_b32 v50, v79 offset:512
	ds_read_b32 v51, v79 offset:576
	ds_read_b64_tr_b16 v[128:129], v72 offset:36864
	ds_read_b64_tr_b16 v[130:131], v72 offset:38016
	ds_read_b64_tr_b16 v[132:133], v72 offset:39168
	ds_read_b64_tr_b16 v[134:135], v72 offset:40320
	ds_read_b64_tr_b16 v[136:137], v75 offset:18432
	ds_read_b64_tr_b16 v[138:139], v75 offset:23040
	ds_read_b64_tr_b16 v[140:141], v75 offset:18464
	ds_read_b64_tr_b16 v[142:143], v75 offset:23072
	ds_read_b64_tr_b16 v[144:145], v75 offset:27648
	ds_read_b64_tr_b16 v[146:147], v75 offset:32256
	ds_read_b64_tr_b16 v[148:149], v75 offset:27680
	ds_read_b64_tr_b16 v[150:151], v75 offset:32288
	s_add_u32 s3, s34, 4
	s_min_u32 s3, s3, 67
	s_cmp_lt_u32 s3, 4
	s_cselect_b32 s4, s16, s17
	s_mul_i32 s5, s3, s15
	s_add_i32 s4, s4, s5
	s_lshl_b32 s5, s4, 14
	s_lshl_b32 s4, s4, 11
	s_add_u32 s40, s18, s5
	s_addc_u32 s41, s19, 0
	s_add_u32 s42, s20, s5
	s_addc_u32 s43, s21, 0
	s_add_u32 s44, s22, s5
	s_addc_u32 s45, s23, 0
	s_add_u32 s46, s24, s4
	s_addc_u32 s47, s25, 0
	s_add_u32 s50, s26, s4
	s_addc_u32 s51, s27, 0
	global_load_dwordx4 v[22:25], v53, s[40:41]
	global_load_dwordx4 v[26:29], v54, s[40:41]
	global_load_dwordx4 v[30:33], v53, s[42:43]
	global_load_dwordx4 v[34:37], v54, s[42:43]
	global_load_dwordx2 v[38:39], v55, s[44:45]
	global_load_dword v40, v56, s[46:47]
	global_load_dword v41, v56, s[50:51]
	s_waitcnt lgkmcnt(6)
	v_mfma_f32_16x16x32_bf16 v[42:45], v[128:131], v[136:139], v[42:45]
	ds_read_b64_tr_b16 v[112:113], v82 offset:0
	ds_read_b64_tr_b16 v[114:115], v82 offset:288
	ds_read_b64_tr_b16 v[116:117], v82 offset:2304
	ds_read_b64_tr_b16 v[118:119], v82 offset:2592
	s_waitcnt lgkmcnt(8)
	v_mfma_f32_16x16x32_bf16 v[46:49], v[128:131], v[140:143], v[46:49]
	ds_read_b64_tr_b16 v[120:121], v82 offset:4608
	ds_read_b64_tr_b16 v[122:123], v82 offset:4896
	ds_read_b64_tr_b16 v[124:125], v82 offset:6912
	ds_read_b64_tr_b16 v[126:127], v82 offset:7200
	s_waitcnt lgkmcnt(10)
	v_mfma_f32_16x16x32_bf16 v[42:45], v[132:135], v[144:147], v[42:45]
	ds_read_b128 v[164:167], v86
	ds_read_b128 v[168:171], v86 offset:1024
	s_waitcnt lgkmcnt(10)
	v_mfma_f32_16x16x32_bf16 v[46:49], v[132:135], v[148:151], v[46:49]
	s_waitcnt lgkmcnt(8)
	v_mfma_f32_16x16x32_bf16 v[172:175], v[112:115], v[96:99], 0
	ds_read_b128 v[200:203], v67 offset:0
	ds_read_b128 v[204:207], v67 offset:64
	s_waitcnt lgkmcnt(8)
	v_mfma_f32_16x16x32_bf16 v[172:175], v[116:119], v[100:103], v[172:175]
	ds_read_b128 v[208:211], v67 offset:128
	ds_read_b128 v[212:215], v67 offset:192
	s_waitcnt lgkmcnt(8)
	v_mfma_f32_16x16x32_bf16 v[172:175], v[120:123], v[104:107], v[172:175]
	s_cmp_eq_u32 s13, 0
	s_cbranch_scc1 .Lsc5_nox_t0
	ds_read_b128 v[216:219], v70 offset:18432
	ds_read_b128 v[220:223], v70 offset:18496
	ds_read_b128 v[224:227], v70 offset:18560
	ds_read_b128 v[228:231], v70 offset:18624

; #define SCAN_BAR() asm volatile("s_waitcnt lgkmcnt(0)\n\ts_barrier" ::: "memory")
; __device__ void scan_phase(LAS unsigned char* lds, const Params& p) {
;     ...
;     for (int item = blockIdx.x; item < 256; item += gridDim.x) {
;     ...
;         SCAN_LOAD(0, k4A, q4A, v4A, rvA, tlA); SCAN_LOAD(1, k4B, q4B, v4B, rvB, tlB); SCAN_LOAD(2, k4C, q4C, v4C, rvC, tlC); SCAN_LOAD(3, k4D, q4D, v4D, rvD, tlD);
;         SCAN_STAGE(0, k4A, q4A, v4A, rvA, tlA); SCAN_LOAD(4, k4A, q4A, v4A, rvA, tlA);
;         SCAN_BAR();
; #pragma unroll 1
;         for (int n0 = 0; n0 < 68; n0 += 4) {
;             SCAN_STAGE(1, k4B, q4B, v4B, rvB, tlB); SCAN_LOAD(min(n0 + 5, 67), k4B, q4B, v4B, rvB, tlB); SCAN_MAT(0, n0); SCAN_BAR();
;             SCAN_STAGE(0, k4C, q4C, v4C, rvC, tlC); SCAN_LOAD(min(n0 + 6, 67), k4C, q4C, v4C, rvC, tlC); SCAN_MAT(1, n0 + 1); SCAN_BAR();
;             SCAN_STAGE(1, k4D, q4D, v4D, rvD, tlD); SCAN_LOAD(min(n0 + 7, 67), k4D, q4D, v4D, rvD, tlD); SCAN_MAT(0, n0 + 2); SCAN_BAR();
;             SCAN_STAGE(0, k4A, q4A, v4A, rvA, tlA); SCAN_LOAD(min(n0 + 8, 67), k4A, q4A, v4A, rvA, tlA); SCAN_MAT(1, n0 + 3); SCAN_BAR();
.Lsc5_noyw_t0:
	s_waitcnt lgkmcnt(0)
	s_barrier
	ds_read_b64_tr_b16 v[128:129], v73 offset:36864
	ds_read_b64_tr_b16 v[130:131], v73 offset:38016
	ds_read_b64_tr_b16 v[132:133], v73 offset:39168
	ds_read_b64_tr_b16 v[134:135], v73 offset:40320
	ds_read_b64_tr_b16 v[136:137], v76 offset:18432
	ds_read_b64_tr_b16 v[138:139], v76 offset:23040
	ds_read_b64_tr_b16 v[140:141], v76 offset:18464
	ds_read_b64_tr_b16 v[142:143], v76 offset:23072
	ds_read_b64_tr_b16 v[144:145], v76 offset:27648
	ds_read_b64_tr_b16 v[146:147], v76 offset:32256
	ds_read_b64_tr_b16 v[148:149], v76 offset:27680
	ds_read_b64_tr_b16 v[150:151], v76 offset:32288
	s_add_u32 s3, s34, 5
	s_min_u32 s3, s3, 67
	s_cmp_lt_u32 s3, 4
	s_cselect_b32 s4, s16, s17
	s_mul_i32 s5, s3, s15
	s_add_i32 s4, s4, s5
	s_lshl_b32 s5, s4, 14
	s_lshl_b32 s4, s4, 11
	s_add_u32 s40, s18, s5
	s_addc_u32 s41, s19, 0
	s_add_u32 s42, s20, s5
	s_addc_u32 s43, s21, 0
	s_add_u32 s44, s22, s5
	s_addc_u32 s45, s23, 0
	s_add_u32 s46, s24, s4
	s_addc_u32 s47, s25, 0
	s_add_u32 s50, s26, s4
	s_addc_u32 s51, s27, 0
	global_load_dwordx4 v[180:183], v53, s[40:41]
	global_load_dwordx4 v[184:187], v54, s[40:41]
	global_load_dwordx4 v[188:191], v53, s[42:43]
	global_load_dwordx4 v[192:195], v54, s[42:43]
	global_load_dwordx2 v[196:197], v55, s[44:45]
	global_load_dword v198, v56, s[46:47]
	global_load_dword v199, v56, s[50:51]
	s_waitcnt lgkmcnt(6)
	v_mfma_f32_16x16x32_bf16 v[42:45], v[128:131], v[136:139], v[42:45]
	ds_read_b64_tr_b16 v[112:113], v83 offset:0
	ds_read_b64_tr_b16 v[114:115], v83 offset:288
	ds_read_b64_tr_b16 v[116:117], v83 offset:2304
	ds_read_b64_tr_b16 v[118:119], v83 offset:2592
	s_waitcnt lgkmcnt(8)
	v_mfma_f32_16x16x32_bf16 v[46:49], v[128:131], v[140:143], v[46:49]
	ds_read_b64_tr_b16 v[120:121], v83 offset:4608
	ds_read_b64_tr_b16 v[122:123], v83 offset:4896
	ds_read_b64_tr_b16 v[124:125], v83 offset:6912
	ds_read_b64_tr_b16 v[126:127], v83 offset:7200
	s_waitcnt lgkmcnt(10)
	v_mfma_f32_16x16x32_bf16 v[42:45], v[132:135], v[144:147], v[42:45]
	ds_read_b128 v[164:167], v87
	ds_read_b128 v[168:171], v87 offset:1024
	s_waitcnt lgkmcnt(10)
	v_mfma_f32_16x16x32_bf16 v[46:49], v[132:135], v[148:151], v[46:49]
	s_waitcnt lgkmcnt(8)
	v_mfma_f32_16x16x32_bf16 v[172:175], v[112:115], v[200:203], 0
	s_waitcnt lgkmcnt(6)
	v_mfma_f32_16x16x32_bf16 v[172:175], v[116:119], v[204:207], v[172:175]
	s_waitcnt lgkmcnt(4)
	v_mfma_f32_16x16x32_bf16 v[172:175], v[120:123], v[208:211], v[172:175]
	s_waitcnt lgkmcnt(2)
	v_mfma_f32_16x16x32_bf16 v[172:175], v[124:127], v[212:215], v[172:175]
	s_waitcnt lgkmcnt(1)
	v_mfma_f32_16x16x32_bf16 v[172:175], v[128:131], v[164:167], v[172:175]
	s_waitcnt lgkmcnt(0)
	s_cmp_eq_u32 s11, 0
	s_cbranch_scc1 .Lsc5_nopv1_t1
	v_mfma_f32_16x16x32_bf16 v[172:175], v[132:135], v[168:171], v[172:175]
.Lsc5_nopv1_t1:
	s_add_u32 s3, s34, 1
	s_cmp_lt_u32 s3, 4
	s_cselect_b32 s4, s16, s17
	s_mul_i32 s5, s3, s15
	s_add_i32 s4, s4, s5
	s_lshl_b32 s4, s4, 16
	s_add_u32 s64, s28, s4
	s_addc_u32 s65, s29, 0
	s_nop 7
	v_cvt_pk_bf16_f32 v176, v172, v173
	v_cvt_pk_bf16_f32 v177, v174, v175
	s_waitcnt vmcnt(16)
	ds_write_b128 v60, v[2:5] offset:0
	ds_write_b128 v60, v[6:9] offset:9216
	ds_write_b128 v60, v[10:13] offset:18432
	ds_write_b128 v60, v[14:17] offset:27648
	ds_write_b64 v63, v[18:19] offset:36864
	v_add_f32_e32 v92, v20, v52
	v_mul_f32_e32 v92, 0x3fb8aa3b, v92
	v_exp_f32_e32 v92, v92
	v_mov_b32_e32 v52, v21
	ds_write_b32 v78, v92 offset:0
	global_store_dwordx2 v57, v[176:177], s[64:65]
	s_waitcnt lgkmcnt(0)
	s_barrier
	s_add_u32 s9, s9, s35
	s_cmp_lt_u32 s9, 0x100
	s_cbranch_scc1 .Lsc5_item

; #define LAS __attribute__((address_space(3)))
; __global__ void __launch_bounds__(NTHR, 2) hymba_fwd(Params p) {
;     extern __shared__ __attribute__((aligned(16))) unsigned char lds_raw[];
;     LAS unsigned char* lds = (LAS unsigned char*)lds_raw;
	.amdhsa_kernel _Z9hymba_fwd6Params
		.amdhsa_group_segment_fixed_size 30720
		.amdhsa_private_segment_fixed_size 0
		.amdhsa_kernarg_size 408
		.amdhsa_user_sgpr_count 2
		.amdhsa_user_sgpr_dispatch_ptr 0
		.amdhsa_user_sgpr_queue_ptr 0
		.amdhsa_user_sgpr_kernarg_segment_ptr 1
		.amdhsa_user_sgpr_dispatch_id 0
		.amdhsa_user_sgpr_kernarg_preload_length 0
		.amdhsa_user_sgpr_kernarg_preload_offset 0
		.amdhsa_user_sgpr_private_segment_size 0
		.amdhsa_uses_dynamic_stack 0
		.amdhsa_enable_private_segment 0
		.amdhsa_system_sgpr_workgroup_id_x 1
		.amdhsa_system_sgpr_workgroup_id_y 0
		.amdhsa_system_sgpr_workgroup_id_z 0
		.amdhsa_system_sgpr_workgroup_info 0
		.amdhsa_system_vgpr_workitem_id 0
		.amdhsa_next_free_vgpr 256
		.amdhsa_next_free_sgpr 100
		.amdhsa_accum_offset 256
		.amdhsa_reserve_vcc 1
		.amdhsa_float_round_mode_32 0
		.amdhsa_float_round_mode_16_64 0
		.amdhsa_float_denorm_mode_32 3
		.amdhsa_float_denorm_mode_16_64 3
		.amdhsa_dx10_clamp 1
		.amdhsa_ieee_mode 1
		.amdhsa_fp16_overflow 0
		.amdhsa_tg_split 0
		.amdhsa_exception_fp_ieee_invalid_op 0
		.amdhsa_exception_fp_denorm_src 0
		.amdhsa_exception_fp_ieee_div_zero 0
		.amdhsa_exception_fp_ieee_overflow 0
		.amdhsa_exception_fp_ieee_underflow 0
		.amdhsa_exception_fp_ieee_inexact 0
		.amdhsa_exception_int_div_zero 0
	.end_amdhsa_kernel

amdhsa.kernels:
  - .agpr_count:     0
    .args:
      - .offset:         0
        .size:           152
        .value_kind:     by_value
      - .offset:         152
        .size:           4
        .value_kind:     hidden_block_count_x
      - .offset:         156
        .size:           4
        .value_kind:     hidden_block_count_y
      - .offset:         160
        .size:           4
        .value_kind:     hidden_block_count_z
      - .offset:         164
        .size:           2
        .value_kind:     hidden_group_size_x
      - .offset:         166
        .size:           2
        .value_kind:     hidden_group_size_y
      - .offset:         168
        .size:           2
        .value_kind:     hidden_group_size_z
      - .offset:         170
        .size:           2
        .value_kind:     hidden_remainder_x
      - .offset:         172
        .size:           2
        .value_kind:     hidden_remainder_y
      - .offset:         174
        .size:           2
        .value_kind:     hidden_remainder_z
      - .offset:         192
        .size:           8
        .value_kind:     hidden_global_offset_x
      - .offset:         200
        .size:           8
        .value_kind:     hidden_global_offset_y
      - .offset:         208
        .size:           8
        .value_kind:     hidden_global_offset_z
      - .offset:         216
        .size:           2
        .value_kind:     hidden_grid_dims
      - .offset:         272
        .size:           4
        .value_kind:     hidden_dynamic_lds_size
    .group_segment_fixed_size: 30720
    .kernarg_segment_align: 8
    .kernarg_segment_size: 408
    .language:       OpenCL C
    .language_version:
      - 2
      - 0
    .max_flat_workgroup_size: 512
    .name:           _Z9hymba_fwd6Params
    .private_segment_fixed_size: 0
    .sgpr_count:     106
    .sgpr_spill_count: 4
    .symbol:         _Z9hymba_fwd6Params.kd
    .uniform_work_group_size: 1
    .uses_dynamic_stack: false
    .vgpr_count:     256
    .vgpr_spill_count: 0
    .wavefront_size: 64
